# stacked attention trims + dead mask-bound setup ops removed (lower bound computed only on the sequence-start path; spacing nop kept in front of the dependent MFMA)
# baseline (speedup 1.0000x reference)
; #define LAS __attribute__((address_space(3)))
; __device__ __forceinline__ s16x4 vtr(LAS const unsigned char* p) { return __builtin_bit_cast(s16x4, __builtin_amdgcn_ds_read_tr16_b64_v4i16((LAS v4i16_t*)p)); }
; __device__ __forceinline__ void att_block(const bf16x8 (&kf)[4], const bf16x8 (&qf)[4], const bf16x8 (&va)[4], f32x16& o0, f32x16& o1, float& mrun, float& lrun, bool domask, int lo_, int hi_) {
;     ...
;     for (int kk = 0; kk < 4; ++kk) st = __builtin_amdgcn_mfma_f32_32x32x16_bf16(kf[kk], qf[kk], st, 0, 0, 0);
;     if (domask) {
;         asm volatile("" : "+v"(lo_), "+v"(hi_));
; #pragma unroll
;         for (int i = 0; i < 16; ++i) { const int ci = (i & 3) + 8 * (i >> 2); st[i] = ((ci - lo_) | (hi_ - ci)) < 0 ? -INFINITY : st[i]; }
;     }
; __device__ __forceinline__ void att_phase(unsigned char* ws, LAS unsigned char* lds, int lane, int wave, int G) {
;     ...
;             asm volatile("s_waitcnt vmcnt(0)" ::: "memory");
;             if (kb < 5) ATT_DMA_KV(P, kb + 1, sb ^ 1);
;             else if (hn) ATT_DMA_KV(N, 0, sb ^ 1);
;             bf16x8 kf[4], va[4];
; #pragma unroll
;             for (int kk = 0; kk < 4; ++kk) kf[kk] = *(LAS const bf16x8*)(kfb + sb * 4096 + (((2 * kk + h) ^ (qc & 7)) << 4));
;             LAS const unsigned char* trs = trb + 8192 + sb * 4096;
; #pragma unroll
;             for (int s = 0; s < 2; ++s) {
;                 const s16x4 lo0 = vtr(trs + (16 * s) * VP), hi0 = vtr(trs + (16 * s + 8) * VP);
;                 const s16x4 lo1 = vtr(trs + (16 * s) * VP + 64), hi1 = vtr(trs + (16 * s + 8) * VP + 64);
;                 va[2 * s] = (bf16x8){lo0[0], lo0[1], lo0[2], lo0[3], hi0[0], hi0[1], hi0[2], hi0[3]};
;                 va[2 * s + 1] = (bf16x8){lo1[0], lo1[1], lo1[2], lo1[3], hi1[0], hi1[1], hi1[2], hi1[3]};
;             }
;             if (kb <= 4) {
;                 att_block(kf, qfA, va, oA0, oA1, mA, lA, kb == 0 || kb == 4 || kminA > 32 * kb, mloA - 4 * h - 32 * kb, qc + 128 - 4 * h - 32 * kb);
.LBB0_80:
	v_add_u32_e32 v0, 0xffffffa0, v191
	v_mul_lo_u32 v0, s56, v0
	v_add_u32_e32 v4, s11, v0
	v_max_i32_e32 v164, 0, v4
	s_add_i32 s57, s33, 0x1000
	s_lshl_b32 s6, s56, 3
	s_waitcnt vmcnt(0)
	v_lshl_add_u32 v2, v164, 7, v180
	s_mov_b32 m0, s57
	s_add_i32 s7, s33, 0x3000
	v_add_u32_e32 v4, s6, v4
	global_load_lds_dwordx4 v2, s[98:99]
	v_lshl_add_u32 v0, v164, 7, v182
	s_mov_b32 m0, s7
	v_max_i32_e32 v164, 0, v4
	global_load_lds_dwordx4 v0, s[100:101]
	v_readlane_b32 s15, v254, 28
	v_lshl_add_u32 v2, v164, 7, v180
	s_mov_b32 m0, s15
	v_readlane_b32 s15, v254, 29
	v_add_u32_e32 v4, s6, v4
	global_load_lds_dwordx4 v2, s[98:99]
	v_lshl_add_u32 v0, v164, 7, v182
	s_mov_b32 m0, s15
	v_max_i32_e32 v164, 0, v4
	global_load_lds_dwordx4 v0, s[100:101]
	s_add_i32 s15, s33, 0x1800
	v_lshl_add_u32 v2, v164, 7, v180
	s_mov_b32 m0, s15
	s_add_i32 s17, s33, 0x3800
	v_add_u32_e32 v51, s6, v4
	global_load_lds_dwordx4 v2, s[98:99]
	v_lshl_add_u32 v0, v164, 7, v182
	s_mov_b32 m0, s17
	v_max_i32_e32 v164, 0, v51
	global_load_lds_dwordx4 v0, s[100:101]
	s_add_i32 s21, s33, 0x1c00
	v_lshl_add_u32 v2, v164, 7, v180
	s_mov_b32 m0, s21
	v_readlane_b32 s59, v254, 30
	global_load_lds_dwordx4 v2, s[98:99]
	v_lshl_add_u32 v0, v164, 7, v182
	s_mov_b32 m0, s59
	v_max_i32_e32 v199, s58, v189
	global_load_lds_dwordx4 v0, s[100:101]
	ds_read_b128 v[0:3], v225
	ds_read_b128 v[16:19], v226
	s_waitcnt lgkmcnt(0)
	v_mfma_f32_32x32x16_bf16 v[0:15], v[0:3], v[128:131], 0
	ds_read_b128 v[20:23], v228
	s_mov_b32 s59, 0xff800000
	v_mfma_f32_32x32x16_bf16 v[0:15], v[16:19], v[124:127], v[0:15]
	ds_read_b128 v[16:19], v227
	ds_read_b64_tr_b16 v[34:35], v229 offset:8192
	ds_read_b64_tr_b16 v[36:37], v229 offset:9216
	ds_read_b64_tr_b16 v[40:41], v229 offset:9280
	ds_read_b64_tr_b16 v[38:39], v229 offset:8256
	ds_read_b64_tr_b16 v[42:43], v229 offset:10240
	ds_read_b64_tr_b16 v[44:45], v229 offset:11264
	ds_read_b64_tr_b16 v[48:49], v229 offset:11328
	ds_read_b64_tr_b16 v[46:47], v229 offset:10304
	s_waitcnt lgkmcnt(8)
	v_mfma_f32_32x32x16_bf16 v[0:15], v[16:19], v[120:123], v[0:15]
	s_waitcnt lgkmcnt(0)
	s_nop 0
	v_mfma_f32_32x32x16_bf16 v[0:15], v[20:23], v[116:119], v[0:15]
	s_nop 6
	s_cmp_lg_u32 s58, 0
	s_cbranch_scc1 .Lmk_slow_0
	s_mov_b32 vcc_lo, 0x1
	s_mov_b32 vcc_hi, 0x1f
	s_mov_b32 s24, 0x3
	s_mov_b32 s25, 0x3f
	s_mov_b32 s26, 0x7
	s_mov_b32 s27, 0x7f
	s_mov_b32 s28, 0xf
	s_mov_b32 s29, 0xff
	s_nop 0
	v_cndmask_b32_e32 v0, v211, v0, vcc
	s_mov_b32 vcc_lo, 0x1ff
	s_mov_b32 vcc_hi, 0x1fff
	v_cndmask_b32_e64 v1, v211, v1, s[24:25]
	s_mov_b32 s24, 0x3ff
	s_mov_b32 s25, 0x3fff
	v_cndmask_b32_e64 v2, v211, v2, s[26:27]
	s_mov_b32 s26, 0x7ff
	s_mov_b32 s27, 0x7fff
	v_cndmask_b32_e64 v3, v211, v3, s[28:29]
	s_mov_b32 s28, 0xfff
	s_mov_b32 s29, 0xffff
	v_cndmask_b32_e32 v4, v211, v4, vcc
	s_mov_b32 vcc_lo, 0x1ffff
	s_mov_b32 vcc_hi, 0x1fffff
	v_cndmask_b32_e64 v5, v211, v5, s[24:25]
	s_mov_b32 s24, 0x3ffff
	s_mov_b32 s25, 0x3fffff
	v_cndmask_b32_e64 v6, v211, v6, s[26:27]
	s_mov_b32 s26, 0x7ffff
	s_mov_b32 s27, 0x7fffff
	v_cndmask_b32_e64 v7, v211, v7, s[28:29]
	s_mov_b32 s28, 0xfffff
	s_mov_b32 s29, 0xffffff
	v_cndmask_b32_e32 v8, v211, v8, vcc
	s_mov_b32 vcc_lo, 0x1ffffff
	s_mov_b32 vcc_hi, 0x1fffffff
	v_cndmask_b32_e64 v9, v211, v9, s[24:25]
	s_mov_b32 s24, 0x3ffffff
	s_mov_b32 s25, 0x3fffffff
	v_cndmask_b32_e64 v10, v211, v10, s[26:27]
	s_mov_b32 s26, 0x7ffffff
	s_mov_b32 s27, 0x7fffffff
	v_cndmask_b32_e64 v11, v211, v11, s[28:29]
	s_mov_b32 s28, 0xfffffff
	s_mov_b32 s29, 0xffffffff
	v_cndmask_b32_e32 v56, v211, v12, vcc
	v_cndmask_b32_e64 v57, v211, v13, s[24:25]
	v_cndmask_b32_e64 v58, v211, v14, s[26:27]
	v_cndmask_b32_e64 v59, v211, v15, s[28:29]
	s_branch .Lmk_done_0
.Lmk_slow_0:
	v_sub_u32_e32 v16, v199, v193
	v_cmp_ge_i32_e32 vcc, 0, v16
	v_cmp_ge_i32_e64 s[24:25], 1, v16
	v_cmp_ge_i32_e64 s[26:27], 2, v16
	v_cmp_ge_i32_e64 s[28:29], 3, v16
	s_nop 0
	v_cndmask_b32_e32 v0, v211, v0, vcc
	v_cmp_ge_i32_e32 vcc, 8, v16
	v_cndmask_b32_e64 v1, v211, v1, s[24:25]
	v_cmp_ge_i32_e64 s[24:25], 9, v16
	v_cndmask_b32_e64 v2, v211, v2, s[26:27]
	v_cmp_ge_i32_e64 s[26:27], 10, v16
	v_cndmask_b32_e64 v3, v211, v3, s[28:29]
	v_cmp_ge_i32_e64 s[28:29], 11, v16
	v_cndmask_b32_e32 v4, v211, v4, vcc
	v_cmp_ge_i32_e32 vcc, 16, v16
	v_cndmask_b32_e64 v5, v211, v5, s[24:25]
	v_cmp_ge_i32_e64 s[24:25], 17, v16
	v_cndmask_b32_e64 v6, v211, v6, s[26:27]
	v_cmp_ge_i32_e64 s[26:27], 18, v16
	v_cndmask_b32_e64 v7, v211, v7, s[28:29]
	v_cmp_ge_i32_e64 s[28:29], 19, v16
	v_cndmask_b32_e32 v8, v211, v8, vcc
	v_cmp_ge_i32_e32 vcc, 24, v16
	v_cndmask_b32_e64 v9, v211, v9, s[24:25]
	v_cmp_ge_i32_e64 s[24:25], 25, v16
	v_cndmask_b32_e64 v10, v211, v10, s[26:27]
	v_cmp_ge_i32_e64 s[26:27], 26, v16
	v_cndmask_b32_e64 v11, v211, v11, s[28:29]
	v_cmp_ge_i32_e64 s[28:29], 27, v16
	v_cndmask_b32_e32 v56, v211, v12, vcc
	v_cndmask_b32_e64 v57, v211, v13, s[24:25]
	v_cndmask_b32_e64 v58, v211, v14, s[26:27]
	v_cndmask_b32_e64 v59, v211, v15, s[28:29]

; __device__ __forceinline__ unsigned pk2(float lo, float hi) { return pg8::cvt_pk_bf16(lo, hi); }
; __device__ __forceinline__ void att_block(const bf16x8 (&kf)[4], const bf16x8 (&qf)[4], const bf16x8 (&va)[4], f32x16& o0, f32x16& o1, float& mrun, float& lrun, bool domask, int lo_, int hi_) {
;     ...
;     float bmax = -INFINITY;
; #pragma unroll
;     for (int i = 0; i < 16; ++i) bmax = fmaxf(bmax, st[i]);
;     bmax = fmaxf(bmax, __shfl_xor(bmax, 32));
;     const float mnew = fmaxf(mrun, bmax);
;     float lsum = 0.f;
; #pragma unroll
;     for (int i = 0; i < 16; ++i) { st[i] = __builtin_amdgcn_exp2f(st[i] - mnew); lsum += st[i]; }
;     lsum += __shfl_xor(lsum, 32);
;     const float alpha = __builtin_amdgcn_exp2f(mrun - mnew);
;     lrun = lrun * alpha + lsum; mrun = mnew;
; #pragma unroll
;     for (int i = 0; i < 16; ++i) { o0[i] *= alpha; o1[i] *= alpha; }
; #pragma unroll
;     for (int s = 0; s < 2; ++s) { v4u w; w.x = pk2(st[8 * s], st[8 * s + 1]); w.y = pk2(st[8 * s + 2], st[8 * s + 3]); w.z = pk2(st[8 * s + 4], st[8 * s + 5]); w.w = pk2(st[8 * s + 6], st[8 * s + 7]);
;         const bf16x8 pb = __builtin_bit_cast(bf16x8, w);
;         o0 = __builtin_amdgcn_mfma_f32_32x32x16_bf16(va[2 * s], pb, o0, 0, 0, 0);
;         o1 = __builtin_amdgcn_mfma_f32_32x32x16_bf16(va[2 * s + 1], pb, o1, 0, 0, 0); }
; __device__ __forceinline__ void att_phase(unsigned char* ws, LAS unsigned char* lds, int lane, int wave, int G) {
;     ...
;             if (kb >= 1) {
;                 att_block(kf, qfB, va, oB0, oB1, mB, lB, kb == 1 || kb == 5 || kminB > 32 * (kb - 1), mloB - 4 * h - 32 * (kb - 1), qc + 128 - 4 * h - 32 * (kb - 1));
.LBB0_82:
	s_mov_b32 s59, 0xff800000
	s_nop 9
	v_max3_f32 v51, v34, s59, v35
	v_max3_f32 v51, v51, v36, v37
	v_max3_f32 v51, v51, v38, v39
	v_max3_f32 v51, v51, v40, v41
	v_max3_f32 v51, v51, v42, v43
	v_max3_f32 v51, v51, v44, v45
	v_max3_f32 v51, v51, v46, v47
	v_max3_f32 v51, v51, v48, v49
	ds_bpermute_b32 v72, v201, v51
	v_max_i32_e32 v237, s14, v189
	s_mov_b32 s60, 0xff800000
	s_waitcnt lgkmcnt(0)
	v_max3_f32 v148, v50, v51, v72
	v_sub_f32_e32 v34, v34, v148
	v_exp_f32_e32 v72, v34
	v_sub_f32_e32 v35, v35, v148
	v_exp_f32_e32 v73, v35
	v_sub_f32_e32 v35, v36, v148
	v_exp_f32_e32 v74, v35
	v_sub_f32_e32 v35, v37, v148
	v_exp_f32_e32 v75, v35
	v_sub_f32_e32 v35, v38, v148
	v_exp_f32_e32 v76, v35
	v_sub_f32_e32 v35, v39, v148
	v_add_f32_e32 v34, v73, v72
	v_exp_f32_e32 v77, v35
	v_sub_f32_e32 v35, v40, v148
	v_add_f32_e32 v34, v74, v34
	v_exp_f32_e32 v78, v35
	v_sub_f32_e32 v35, v41, v148
	v_add_f32_e32 v34, v75, v34
	v_exp_f32_e32 v79, v35
	v_sub_f32_e32 v35, v42, v148
	v_add_f32_e32 v34, v76, v34
	v_exp_f32_e32 v80, v35
	v_sub_f32_e32 v35, v43, v148
	v_add_f32_e32 v34, v77, v34
	v_exp_f32_e32 v81, v35
	v_sub_f32_e32 v35, v44, v148
	v_add_f32_e32 v34, v78, v34
	v_exp_f32_e32 v82, v35
	v_sub_f32_e32 v35, v45, v148
	v_add_f32_e32 v34, v79, v34
	v_exp_f32_e32 v83, v35
	v_sub_f32_e32 v35, v46, v148
	v_add_f32_e32 v34, v80, v34
	v_exp_f32_e32 v96, v35
	v_sub_f32_e32 v35, v47, v148
	v_add_f32_e32 v34, v81, v34
	v_exp_f32_e32 v97, v35
	v_sub_f32_e32 v35, v48, v148
	v_add_f32_e32 v34, v82, v34
	v_exp_f32_e32 v98, v35
	v_sub_f32_e32 v35, v49, v148
	v_add_f32_e32 v34, v83, v34
	v_exp_f32_e32 v99, v35
	v_add_f32_e32 v34, v96, v34
	v_add_f32_e32 v34, v97, v34
	v_add_f32_e32 v34, v98, v34
	v_add_f32_e32 v235, v99, v34
	v_sub_f32_e32 v34, v50, v148
	v_exp_f32_e32 v188, v34
	ds_bpermute_b32 v236, v201, v235
	v_pk_mul_f32 v[34:35], v[32:33], v[188:189] op_sel_hi:[1,0]
	v_pk_mul_f32 v[32:33], v[30:31], v[188:189] op_sel_hi:[1,0]
	v_pk_mul_f32 v[30:31], v[28:29], v[188:189] op_sel_hi:[1,0]
	v_pk_mul_f32 v[28:29], v[26:27], v[188:189] op_sel_hi:[1,0]
	v_pk_mul_f32 v[26:27], v[24:25], v[188:189] op_sel_hi:[1,0]
	v_pk_mul_f32 v[24:25], v[22:23], v[188:189] op_sel_hi:[1,0]
	v_pk_mul_f32 v[22:23], v[20:21], v[188:189] op_sel_hi:[1,0]
	v_pk_mul_f32 v[20:21], v[18:19], v[188:189] op_sel_hi:[1,0]
	v_pk_mul_f32 v[50:51], v[16:17], v[188:189] op_sel_hi:[1,0]
	v_pk_mul_f32 v[48:49], v[14:15], v[188:189] op_sel_hi:[1,0]
	v_pk_mul_f32 v[46:47], v[12:13], v[188:189] op_sel_hi:[1,0]
	v_pk_mul_f32 v[44:45], v[10:11], v[188:189] op_sel_hi:[1,0]
	v_pk_mul_f32 v[42:43], v[8:9], v[188:189] op_sel_hi:[1,0]
	v_pk_mul_f32 v[40:41], v[6:7], v[188:189] op_sel_hi:[1,0]
	v_pk_mul_f32 v[38:39], v[4:5], v[188:189] op_sel_hi:[1,0]
	v_pk_mul_f32 v[36:37], v[2:3], v[188:189] op_sel_hi:[1,0]
	v_cvt_pk_bf16_f32 v2, v72, v73
	v_cvt_pk_bf16_f32 v3, v74, v75
	v_cvt_pk_bf16_f32 v4, v76, v77
	v_cvt_pk_bf16_f32 v5, v78, v79
	s_nop 1
	v_mfma_f32_32x32x16_bf16 v[20:35], v[52:55], v[2:5], v[20:35]
	s_waitcnt lgkmcnt(0)
	v_mfma_f32_32x32x16_bf16 v[36:51], v[92:95], v[2:5], v[36:51]
	v_cvt_pk_bf16_f32 v2, v80, v81
	v_cvt_pk_bf16_f32 v3, v82, v83
	v_cvt_pk_bf16_f32 v4, v96, v97
	v_cvt_pk_bf16_f32 v5, v98, v99
	s_nop 1
	v_mfma_f32_32x32x16_bf16 v[20:35], v[88:91], v[2:5], v[20:35]
	v_mfma_f32_32x32x16_bf16 v[36:51], v[84:87], v[2:5], v[36:51]
	v_mfma_f32_32x32x16_bf16 v[2:17], v[68:71], v[112:115], 0
	v_mfma_f32_32x32x16_bf16 v[2:17], v[64:67], v[108:111], v[2:17]
	v_mfma_f32_32x32x16_bf16 v[2:17], v[60:63], v[104:107], v[2:17]
	v_mfma_f32_32x32x16_bf16 v[2:17], v[56:59], v[100:103], v[2:17]
	s_nop 4
	s_cmp_lg_u32 s14, 0
	s_cbranch_scc1 .Lmk_slow_2
	s_mov_b32 vcc_lo, 0x1
	s_mov_b32 vcc_hi, 0x1f
	s_mov_b32 s24, 0x3
	s_mov_b32 s25, 0x3f
	s_mov_b32 s26, 0x7
	s_mov_b32 s27, 0x7f
	s_mov_b32 s28, 0xf
	s_mov_b32 s29, 0xff
	s_nop 2
	v_cndmask_b32_e32 v2, v211, v2, vcc
	s_mov_b32 vcc_lo, 0x1ff
	s_mov_b32 vcc_hi, 0x1fff
	v_cndmask_b32_e64 v3, v211, v3, s[24:25]
	s_mov_b32 s24, 0x3ff
	s_mov_b32 s25, 0x3fff
	v_cndmask_b32_e64 v4, v211, v4, s[26:27]
	s_mov_b32 s26, 0x7ff
	s_mov_b32 s27, 0x7fff
	v_cndmask_b32_e64 v5, v211, v5, s[28:29]
	s_mov_b32 s28, 0xfff
	s_mov_b32 s29, 0xffff
	v_cndmask_b32_e32 v6, v211, v6, vcc
	s_mov_b32 vcc_lo, 0x1ffff
	s_mov_b32 vcc_hi, 0x1fffff
	v_cndmask_b32_e64 v7, v211, v7, s[24:25]
	s_mov_b32 s24, 0x3ffff
	s_mov_b32 s25, 0x3fffff
	v_cndmask_b32_e64 v8, v211, v8, s[26:27]
	s_mov_b32 s26, 0x7ffff
	s_mov_b32 s27, 0x7fffff
	v_cndmask_b32_e64 v9, v211, v9, s[28:29]
	s_mov_b32 s28, 0xfffff
	s_mov_b32 s29, 0xffffff
	v_cndmask_b32_e32 v10, v211, v10, vcc
	s_mov_b32 vcc_lo, 0x1ffffff
	s_mov_b32 vcc_hi, 0x1fffffff
	v_cndmask_b32_e64 v11, v211, v11, s[24:25]
	s_mov_b32 s24, 0x3ffffff
	s_mov_b32 s25, 0x3fffffff
	v_cndmask_b32_e64 v12, v211, v12, s[26:27]
	s_mov_b32 s26, 0x7ffffff
	s_mov_b32 s27, 0x7fffffff
	v_cndmask_b32_e64 v13, v211, v13, s[28:29]
	s_mov_b32 s28, 0xfffffff
	s_mov_b32 s29, 0xffffffff
	v_cndmask_b32_e32 v14, v211, v14, vcc
	v_cndmask_b32_e64 v15, v211, v15, s[24:25]
	v_cndmask_b32_e64 v16, v211, v16, s[26:27]
	v_cndmask_b32_e64 v17, v211, v17, s[28:29]
	s_branch .Lmk_done_2
.Lmk_slow_2:
	v_sub_u32_e32 v18, v237, v193
	v_cmp_ge_i32_e32 vcc, 0, v18
	v_cmp_ge_i32_e64 s[24:25], 1, v18
	v_cmp_ge_i32_e64 s[26:27], 2, v18
	v_cmp_ge_i32_e64 s[28:29], 3, v18
	s_nop 2
	v_cndmask_b32_e32 v2, v211, v2, vcc
	v_cmp_ge_i32_e32 vcc, 8, v18
	v_cndmask_b32_e64 v3, v211, v3, s[24:25]
	v_cmp_ge_i32_e64 s[24:25], 9, v18
	v_cndmask_b32_e64 v4, v211, v4, s[26:27]
	v_cmp_ge_i32_e64 s[26:27], 10, v18
	v_cndmask_b32_e64 v5, v211, v5, s[28:29]
	v_cmp_ge_i32_e64 s[28:29], 11, v18
	v_cndmask_b32_e32 v6, v211, v6, vcc
	v_cmp_ge_i32_e32 vcc, 16, v18
	v_cndmask_b32_e64 v7, v211, v7, s[24:25]
	v_cmp_ge_i32_e64 s[24:25], 17, v18
	v_cndmask_b32_e64 v8, v211, v8, s[26:27]
	v_cmp_ge_i32_e64 s[26:27], 18, v18
	v_cndmask_b32_e64 v9, v211, v9, s[28:29]
	v_cmp_ge_i32_e64 s[28:29], 19, v18
	v_cndmask_b32_e32 v10, v211, v10, vcc
	v_cmp_ge_i32_e32 vcc, 24, v18
	v_cndmask_b32_e64 v11, v211, v11, s[24:25]
	v_cmp_ge_i32_e64 s[24:25], 25, v18
	v_cndmask_b32_e64 v12, v211, v12, s[26:27]
	v_cmp_ge_i32_e64 s[26:27], 26, v18
	v_cndmask_b32_e64 v13, v211, v13, s[28:29]
	v_cmp_ge_i32_e64 s[28:29], 27, v18
	v_cndmask_b32_e32 v14, v211, v14, vcc
	v_cndmask_b32_e64 v15, v211, v15, s[24:25]
	v_cndmask_b32_e64 v16, v211, v16, s[26:27]
	v_cndmask_b32_e64 v17, v211, v17, s[28:29]

; #define LAS __attribute__((address_space(3)))
; __device__ __forceinline__ void att_block(const bf16x8 (&kf)[4], const bf16x8 (&qf)[4], const bf16x8 (&va)[4], f32x16& o0, f32x16& o1, float& mrun, float& lrun, bool domask, int lo_, int hi_) {
;     ...
;     float bmax = -INFINITY;
; #pragma unroll
;     for (int i = 0; i < 16; ++i) bmax = fmaxf(bmax, st[i]);
;     bmax = fmaxf(bmax, __shfl_xor(bmax, 32));
;     const float mnew = fmaxf(mrun, bmax);
;     float lsum = 0.f;
; #pragma unroll
;     for (int i = 0; i < 16; ++i) { st[i] = __builtin_amdgcn_exp2f(st[i] - mnew); lsum += st[i]; }
;     lsum += __shfl_xor(lsum, 32);
;     const float alpha = __builtin_amdgcn_exp2f(mrun - mnew);
;     lrun = lrun * alpha + lsum; mrun = mnew;
; #pragma unroll
;     for (int i = 0; i < 16; ++i) { o0[i] *= alpha; o1[i] *= alpha; }
; #pragma unroll
;     for (int s = 0; s < 2; ++s) { v4u w; w.x = pk2(st[8 * s], st[8 * s + 1]); w.y = pk2(st[8 * s + 2], st[8 * s + 3]); w.z = pk2(st[8 * s + 4], st[8 * s + 5]); w.w = pk2(st[8 * s + 6], st[8 * s + 7]);
;         const bf16x8 pb = __builtin_bit_cast(bf16x8, w);
;         o0 = __builtin_amdgcn_mfma_f32_32x32x16_bf16(va[2 * s], pb, o0, 0, 0, 0);
;         o1 = __builtin_amdgcn_mfma_f32_32x32x16_bf16(va[2 * s + 1], pb, o1, 0, 0, 0); }
; __device__ __forceinline__ void att_phase(unsigned char* ws, LAS unsigned char* lds, int lane, int wave, int G) {
;     ...
;             asm volatile("s_waitcnt vmcnt(0)" ::: "memory");
;             if (kb < 5) ATT_DMA_KV(P, kb + 1, sb ^ 1);
;             else if (hn) ATT_DMA_KV(N, 0, sb ^ 1);
;             bf16x8 kf[4], va[4];
; #pragma unroll
;             for (int kk = 0; kk < 4; ++kk) kf[kk] = *(LAS const bf16x8*)(kfb + sb * 4096 + (((2 * kk + h) ^ (qc & 7)) << 4));
;             LAS const unsigned char* trs = trb + 8192 + sb * 4096;
; #pragma unroll
;             for (int s = 0; s < 2; ++s) {
;                 const s16x4 lo0 = vtr(trs + (16 * s) * VP), hi0 = vtr(trs + (16 * s + 8) * VP);
;                 const s16x4 lo1 = vtr(trs + (16 * s) * VP + 64), hi1 = vtr(trs + (16 * s + 8) * VP + 64);
;                 va[2 * s] = (bf16x8){lo0[0], lo0[1], lo0[2], lo0[3], hi0[0], hi0[1], hi0[2], hi0[3]};
;                 va[2 * s + 1] = (bf16x8){lo1[0], lo1[1], lo1[2], lo1[3], hi1[0], hi1[1], hi1[2], hi1[3]};
;             }
.LBB0_90:
	v_mul_lo_u32 v84, s52, v189
	s_mov_b32 s58, 0xff800000
	v_add_u32_e32 v198, s53, v84
	s_nop 7
	v_max3_f32 v84, v68, s58, v69
	v_max3_f32 v84, v84, v70, v71
	v_max3_f32 v84, v84, v72, v73
	v_max3_f32 v84, v84, v74, v75
	v_max3_f32 v84, v84, v76, v77
	v_max3_f32 v84, v84, v78, v79
	v_max3_f32 v84, v84, v80, v81
	v_max3_f32 v84, v84, v82, v83
	ds_bpermute_b32 v85, v201, v84
	s_waitcnt lgkmcnt(0)
	s_waitcnt lgkmcnt(0)
	v_max3_f32 v245, v148, v84, v85
	v_sub_f32_e32 v68, v68, v245
	v_exp_f32_e32 v149, v68
	v_sub_f32_e32 v69, v69, v245
	v_exp_f32_e32 v150, v69
	v_sub_f32_e32 v69, v70, v245
	v_exp_f32_e32 v151, v69
	v_sub_f32_e32 v69, v71, v245
	v_exp_f32_e32 v152, v69
	v_sub_f32_e32 v69, v72, v245
	v_exp_f32_e32 v153, v69
	v_sub_f32_e32 v69, v73, v245
	v_add_f32_e32 v68, v150, v149
	v_exp_f32_e32 v154, v69
	v_sub_f32_e32 v69, v74, v245
	v_add_f32_e32 v68, v151, v68
	v_exp_f32_e32 v155, v69
	v_sub_f32_e32 v69, v75, v245
	v_add_f32_e32 v68, v152, v68
	v_exp_f32_e32 v156, v69
	v_sub_f32_e32 v69, v76, v245
	v_add_f32_e32 v68, v153, v68
	v_exp_f32_e32 v157, v69
	v_sub_f32_e32 v69, v77, v245
	v_add_f32_e32 v68, v154, v68
	v_exp_f32_e32 v158, v69
	v_sub_f32_e32 v69, v78, v245
	v_add_f32_e32 v68, v155, v68
	v_exp_f32_e32 v159, v69
	v_sub_f32_e32 v69, v79, v245
	v_add_f32_e32 v68, v156, v68
	v_exp_f32_e32 v160, v69
	v_sub_f32_e32 v69, v80, v245
	v_add_f32_e32 v68, v157, v68
	v_exp_f32_e32 v161, v69
	v_sub_f32_e32 v69, v81, v245
	v_add_f32_e32 v68, v158, v68
	v_exp_f32_e32 v162, v69
	v_sub_f32_e32 v69, v82, v245
	v_add_f32_e32 v68, v159, v68
	v_exp_f32_e32 v163, v69
	v_sub_f32_e32 v69, v83, v245
	v_add_f32_e32 v68, v160, v68
	v_exp_f32_e32 v164, v69
	v_add_f32_e32 v68, v161, v68
	v_add_f32_e32 v68, v162, v68
	v_add_f32_e32 v68, v163, v68
	v_add_f32_e32 v241, v164, v68
	v_sub_f32_e32 v68, v148, v245
	v_exp_f32_e32 v194, v68
	ds_bpermute_b32 v242, v201, v241
	v_pk_mul_f32 v[82:83], v[50:51], v[194:195] op_sel_hi:[1,0]
	v_pk_mul_f32 v[80:81], v[48:49], v[194:195] op_sel_hi:[1,0]
	v_pk_mul_f32 v[78:79], v[46:47], v[194:195] op_sel_hi:[1,0]
	v_pk_mul_f32 v[76:77], v[44:45], v[194:195] op_sel_hi:[1,0]
	v_pk_mul_f32 v[74:75], v[42:43], v[194:195] op_sel_hi:[1,0]
	v_pk_mul_f32 v[72:73], v[40:41], v[194:195] op_sel_hi:[1,0]
	v_pk_mul_f32 v[70:71], v[38:39], v[194:195] op_sel_hi:[1,0]
	v_pk_mul_f32 v[68:69], v[36:37], v[194:195] op_sel_hi:[1,0]
	v_pk_mul_f32 v[98:99], v[66:67], v[194:195] op_sel_hi:[1,0]
	v_pk_mul_f32 v[96:97], v[64:65], v[194:195] op_sel_hi:[1,0]
	v_pk_mul_f32 v[94:95], v[62:63], v[194:195] op_sel_hi:[1,0]
	v_pk_mul_f32 v[92:93], v[60:61], v[194:195] op_sel_hi:[1,0]
	v_pk_mul_f32 v[90:91], v[58:59], v[194:195] op_sel_hi:[1,0]
	v_pk_mul_f32 v[88:89], v[56:57], v[194:195] op_sel_hi:[1,0]
	v_pk_mul_f32 v[86:87], v[54:55], v[194:195] op_sel_hi:[1,0]
	v_pk_mul_f32 v[84:85], v[52:53], v[194:195] op_sel_hi:[1,0]
	v_cvt_pk_bf16_f32 v36, v149, v150
	v_cvt_pk_bf16_f32 v37, v151, v152
	v_cvt_pk_bf16_f32 v38, v153, v154
	v_cvt_pk_bf16_f32 v39, v155, v156
	s_nop 1
	v_mfma_f32_32x32x16_bf16 v[68:83], v[144:147], v[36:39], v[68:83]
	v_mfma_f32_32x32x16_bf16 v[84:99], v[140:143], v[36:39], v[84:99]
	v_cvt_pk_bf16_f32 v36, v157, v158
	v_cvt_pk_bf16_f32 v37, v159, v160
	v_cvt_pk_bf16_f32 v38, v161, v162
	v_cvt_pk_bf16_f32 v39, v163, v164
	s_nop 1
	v_mfma_f32_32x32x16_bf16 v[68:83], v[136:139], v[36:39], v[68:83]
	v_mfma_f32_32x32x16_bf16 v[84:99], v[132:135], v[36:39], v[84:99]
	v_mul_lo_u32 v36, s56, v222
	v_add_u32_e32 v40, s11, v36
	v_max_i32_e32 v164, 0, v40
	s_waitcnt vmcnt(0)
	v_lshl_add_u32 v38, v164, 7, v180
	s_mov_b32 m0, s57
	v_add_u32_e32 v40, s6, v40
	global_load_lds_dwordx4 v38, s[98:99]
	v_lshl_add_u32 v36, v164, 7, v182
	s_mov_b32 m0, s7
	v_max_i32_e32 v164, 0, v40
	global_load_lds_dwordx4 v36, s[100:101]
	v_readlane_b32 s7, v254, 28
	v_lshl_add_u32 v38, v164, 7, v180
	s_mov_b32 m0, s7
	v_readlane_b32 s7, v254, 29
	v_add_u32_e32 v40, s6, v40
	global_load_lds_dwordx4 v38, s[98:99]
	v_lshl_add_u32 v36, v164, 7, v182
	s_mov_b32 m0, s7
	v_max_i32_e32 v164, 0, v40
	global_load_lds_dwordx4 v36, s[100:101]
	v_lshl_add_u32 v38, v164, 7, v180
	s_mov_b32 m0, s15
	v_lshl_add_u32 v36, v164, 7, v182
	global_load_lds_dwordx4 v38, s[98:99]
	s_mov_b32 m0, s17
	global_load_lds_dwordx4 v36, s[100:101]
	v_add_u32_e32 v36, s6, v40
	v_max_i32_e32 v164, 0, v36
	v_lshl_add_u32 v38, v164, 7, v180
	s_mov_b32 m0, s21
	v_readlane_b32 s6, v254, 30
	global_load_lds_dwordx4 v38, s[98:99]
	v_lshl_add_u32 v36, v164, 7, v182
	s_mov_b32 m0, s6
	global_load_lds_dwordx4 v36, s[100:101]
	ds_read_b128 v[160:163], v225
	ds_read_b128 v[156:159], v226
	ds_read_b128 v[152:155], v227
	ds_read_b128 v[148:151], v228
	ds_read_b64_tr_b16 v[144:145], v229 offset:8192
	ds_read_b64_tr_b16 v[146:147], v229 offset:9216
	ds_read_b64_tr_b16 v[140:141], v229 offset:8256
	ds_read_b64_tr_b16 v[142:143], v229 offset:9280
	ds_read_b64_tr_b16 v[136:137], v229 offset:10240
	ds_read_b64_tr_b16 v[138:139], v229 offset:11264
	ds_read_b64_tr_b16 v[132:133], v229 offset:10304
	ds_read_b64_tr_b16 v[134:135], v229 offset:11328
	s_waitcnt lgkmcnt(0)
; __device__ __forceinline__ unsigned pk2(float lo, float hi) { return pg8::cvt_pk_bf16(lo, hi); }
; #define ATT_LOAD_Q(dst, J, set) do { const int qp_ = (J).pos0 + (32 * (set) + qc) * (J).d; _Pragma("unroll") for (int kk_ = 0; kk_ < 4; ++kk_) dst[kk_] = gld<bf16x8>(Qa + ((J).hb + (size_t)qp_) * 64 + 8 * h + 16 * kk_); } while (0)
; __device__ __forceinline__ void att_block(const bf16x8 (&kf)[4], const bf16x8 (&qf)[4], const bf16x8 (&va)[4], f32x16& o0, f32x16& o1, float& mrun, float& lrun, bool domask, int lo_, int hi_) {
;     f32x16 st;
; #pragma unroll
;     for (int i = 0; i < 16; ++i) st[i] = 0.f;
; #pragma unroll
;     for (int kk = 0; kk < 4; ++kk) st = __builtin_amdgcn_mfma_f32_32x32x16_bf16(kf[kk], qf[kk], st, 0, 0, 0);
;     if (domask) {
;         asm volatile("" : "+v"(lo_), "+v"(hi_));
; #pragma unroll
;         for (int i = 0; i < 16; ++i) { const int ci = (i & 3) + 8 * (i >> 2); st[i] = ((ci - lo_) | (hi_ - ci)) < 0 ? -INFINITY : st[i]; }
;     }
;     float bmax = -INFINITY;
; #pragma unroll
;     for (int i = 0; i < 16; ++i) bmax = fmaxf(bmax, st[i]);
;     bmax = fmaxf(bmax, __shfl_xor(bmax, 32));
;     const float mnew = fmaxf(mrun, bmax);
;     float lsum = 0.f;
; #pragma unroll
;     for (int i = 0; i < 16; ++i) { st[i] = __builtin_amdgcn_exp2f(st[i] - mnew); lsum += st[i]; }
;     lsum += __shfl_xor(lsum, 32);
;     const float alpha = __builtin_amdgcn_exp2f(mrun - mnew);
;     lrun = lrun * alpha + lsum; mrun = mnew;
; #pragma unroll
;     for (int i = 0; i < 16; ++i) { o0[i] *= alpha; o1[i] *= alpha; }
; #pragma unroll
;     for (int s = 0; s < 2; ++s) { v4u w; w.x = pk2(st[8 * s], st[8 * s + 1]); w.y = pk2(st[8 * s + 2], st[8 * s + 3]); w.z = pk2(st[8 * s + 4], st[8 * s + 5]); w.w = pk2(st[8 * s + 6], st[8 * s + 7]);
;         const bf16x8 pb = __builtin_bit_cast(bf16x8, w);
;         o0 = __builtin_amdgcn_mfma_f32_32x32x16_bf16(va[2 * s], pb, o0, 0, 0, 0);
;         o1 = __builtin_amdgcn_mfma_f32_32x32x16_bf16(va[2 * s + 1], pb, o1, 0, 0, 0); }
; }
; __device__ __forceinline__ void att_phase(unsigned char* ws, LAS unsigned char* lds, int lane, int wave, int G) {
;     ...
;             if (kb <= 4) {
;                 att_block(kf, qfA, va, oA0, oA1, mA, lA, kb == 0 || kb == 4 || kminA > 32 * kb, mloA - 4 * h - 32 * kb, qc + 128 - 4 * h - 32 * kb);
;                 if (kb == 4 && hn) ATT_LOAD_Q(qfA, N, 0);
	v_mfma_f32_32x32x16_bf16 v[36:51], v[160:163], v[128:131], 0
	s_nop 0
	v_mfma_f32_32x32x16_bf16 v[36:51], v[156:159], v[124:127], v[36:51]
	v_mfma_f32_32x32x16_bf16 v[36:51], v[152:155], v[120:123], v[36:51]
	v_mfma_f32_32x32x16_bf16 v[36:51], v[148:151], v[116:119], v[36:51]
	s_nop 11
	s_mov_b32 vcc_lo, 0xffffffff
	s_mov_b32 vcc_hi, 0xfffffff0
	s_mov_b32 s24, 0xfffffffe
	s_mov_b32 s25, 0xffffffe0
	s_mov_b32 s26, 0xfffffffc
	s_mov_b32 s27, 0xffffffc0
	s_mov_b32 s28, 0xfffffff8
	s_mov_b32 s29, 0xffffff80
	v_cndmask_b32_e32 v36, v211, v36, vcc
	s_mov_b32 vcc_lo, 0xffffff00
	s_mov_b32 vcc_hi, 0xfffff000
	v_cndmask_b32_e64 v37, v211, v37, s[24:25]
	s_mov_b32 s24, 0xfffffe00
	s_mov_b32 s25, 0xffffe000
	v_cndmask_b32_e64 v38, v211, v38, s[26:27]
	s_mov_b32 s26, 0xfffffc00
	s_mov_b32 s27, 0xffffc000
	v_cndmask_b32_e64 v39, v211, v39, s[28:29]
	s_mov_b32 s28, 0xfffff800
	s_mov_b32 s29, 0xffff8000
	v_cndmask_b32_e32 v40, v211, v40, vcc
	s_mov_b32 vcc_lo, 0xffff0000
	s_mov_b32 vcc_hi, 0xfff00000
	v_cndmask_b32_e64 v41, v211, v41, s[24:25]
	s_mov_b32 s24, 0xfffe0000
	s_mov_b32 s25, 0xffe00000
	v_cndmask_b32_e64 v42, v211, v42, s[26:27]
	s_mov_b32 s26, 0xfffc0000
	s_mov_b32 s27, 0xffc00000
	v_cndmask_b32_e64 v43, v211, v43, s[28:29]
	s_mov_b32 s28, 0xfff80000
	s_mov_b32 s29, 0xff800000
	v_cndmask_b32_e32 v44, v211, v44, vcc
	s_mov_b32 vcc_lo, 0xff000000
	s_mov_b32 vcc_hi, 0xf0000000
	v_cndmask_b32_e64 v45, v211, v45, s[24:25]
	s_mov_b32 s24, 0xfe000000
	s_mov_b32 s25, 0xe0000000
	v_cndmask_b32_e64 v46, v211, v46, s[26:27]
	s_mov_b32 s26, 0xfc000000
	s_mov_b32 s27, 0xc0000000
	v_cndmask_b32_e64 v47, v211, v47, s[28:29]
	s_mov_b32 s28, 0xf8000000
	s_mov_b32 s29, 0x80000000
	v_cndmask_b32_e32 v48, v211, v48, vcc
	v_cndmask_b32_e64 v49, v211, v49, s[24:25]
	v_cndmask_b32_e64 v50, v211, v50, s[26:27]
	v_cndmask_b32_e64 v51, v211, v51, s[28:29]
	s_nop 0
	v_max3_f32 v52, v36, s58, v37
	v_max3_f32 v52, v52, v38, v39
	v_max3_f32 v52, v52, v40, v41
	v_max3_f32 v52, v52, v42, v43
	v_max3_f32 v52, v52, v44, v45
	v_max3_f32 v52, v52, v46, v47
	v_max3_f32 v52, v52, v48, v49
	v_max3_f32 v52, v52, v50, v51
	ds_bpermute_b32 v53, v201, v52
	s_andn2_b64 vcc, exec, s[2:3]
	s_waitcnt lgkmcnt(0)
	v_max3_f32 v200, v202, v52, v53
	v_sub_f32_e32 v36, v36, v200
	v_exp_f32_e32 v164, v36
	v_sub_f32_e32 v37, v37, v200
	v_exp_f32_e32 v166, v37
	v_sub_f32_e32 v37, v38, v200
	v_exp_f32_e32 v167, v37
	v_sub_f32_e32 v37, v39, v200
	v_exp_f32_e32 v199, v37
	v_sub_f32_e32 v37, v40, v200
	v_exp_f32_e32 v248, v37
	v_sub_f32_e32 v37, v41, v200
	v_add_f32_e32 v36, v166, v164
	v_exp_f32_e32 v249, v37
	v_sub_f32_e32 v37, v42, v200
	v_add_f32_e32 v36, v167, v36
	v_exp_f32_e32 v250, v37
	v_sub_f32_e32 v37, v43, v200
	v_add_f32_e32 v36, v199, v36
	v_exp_f32_e32 v251, v37
	v_sub_f32_e32 v37, v44, v200
	v_add_f32_e32 v36, v248, v36
	v_exp_f32_e32 v252, v37
	v_sub_f32_e32 v37, v45, v200
	v_add_f32_e32 v36, v249, v36
	v_exp_f32_e32 v203, v37
	v_sub_f32_e32 v37, v46, v200
	v_add_f32_e32 v36, v250, v36
	v_exp_f32_e32 v168, v37
	v_sub_f32_e32 v37, v47, v200
	v_add_f32_e32 v36, v251, v36
	v_exp_f32_e32 v169, v37
	v_sub_f32_e32 v37, v48, v200
	v_add_f32_e32 v36, v252, v36
	v_exp_f32_e32 v212, v37
	v_sub_f32_e32 v37, v49, v200
	v_add_f32_e32 v36, v203, v36
	v_exp_f32_e32 v209, v37
	v_sub_f32_e32 v37, v50, v200
	v_add_f32_e32 v36, v168, v36
	v_exp_f32_e32 v197, v37
	v_sub_f32_e32 v37, v51, v200
	v_add_f32_e32 v36, v169, v36
	v_exp_f32_e32 v195, v37
	v_add_f32_e32 v36, v212, v36
	v_add_f32_e32 v36, v209, v36
	v_add_f32_e32 v36, v197, v36
	v_add_f32_e32 v246, v195, v36
	v_sub_f32_e32 v36, v202, v200
	v_exp_f32_e32 v202, v36
	ds_bpermute_b32 v247, v201, v246
	v_pk_mul_f32 v[66:67], v[18:19], v[202:203] op_sel_hi:[1,0]
	v_pk_mul_f32 v[64:65], v[16:17], v[202:203] op_sel_hi:[1,0]
	v_pk_mul_f32 v[62:63], v[14:15], v[202:203] op_sel_hi:[1,0]
	v_pk_mul_f32 v[60:61], v[12:13], v[202:203] op_sel_hi:[1,0]
	v_pk_mul_f32 v[58:59], v[10:11], v[202:203] op_sel_hi:[1,0]
	v_pk_mul_f32 v[56:57], v[8:9], v[202:203] op_sel_hi:[1,0]
	v_pk_mul_f32 v[54:55], v[6:7], v[202:203] op_sel_hi:[1,0]
	v_pk_mul_f32 v[52:53], v[4:5], v[202:203] op_sel_hi:[1,0]
	v_pk_mul_f32 v[50:51], v[34:35], v[202:203] op_sel_hi:[1,0]
	v_pk_mul_f32 v[48:49], v[32:33], v[202:203] op_sel_hi:[1,0]
	v_pk_mul_f32 v[46:47], v[30:31], v[202:203] op_sel_hi:[1,0]
	v_pk_mul_f32 v[44:45], v[28:29], v[202:203] op_sel_hi:[1,0]
	v_pk_mul_f32 v[42:43], v[26:27], v[202:203] op_sel_hi:[1,0]
	v_pk_mul_f32 v[40:41], v[24:25], v[202:203] op_sel_hi:[1,0]
	v_pk_mul_f32 v[38:39], v[22:23], v[202:203] op_sel_hi:[1,0]
	v_pk_mul_f32 v[36:37], v[20:21], v[202:203] op_sel_hi:[1,0]
	v_cvt_pk_bf16_f32 v4, v164, v166
	v_cvt_pk_bf16_f32 v5, v167, v199
	v_cvt_pk_bf16_f32 v6, v248, v249
	v_cvt_pk_bf16_f32 v7, v250, v251
	s_nop 1
	v_mfma_f32_32x32x16_bf16 v[52:67], v[144:147], v[4:7], v[52:67]
	v_mfma_f32_32x32x16_bf16 v[36:51], v[140:143], v[4:7], v[36:51]
	v_cvt_pk_bf16_f32 v4, v252, v203
	v_cvt_pk_bf16_f32 v5, v168, v169
	v_cvt_pk_bf16_f32 v6, v212, v209
	v_cvt_pk_bf16_f32 v7, v197, v195
	s_nop 1
	v_mfma_f32_32x32x16_bf16 v[52:67], v[136:139], v[4:7], v[52:67]
	v_mfma_f32_32x32x16_bf16 v[36:51], v[132:135], v[4:7], v[36:51]
	v_cndmask_b32_e64 v4, 0, 1, s[2:3]
	v_cmp_ne_u32_e64 s[6:7], 1, v4
	s_cbranch_vccnz .LBB0_92
	v_ashrrev_i32_e32 v199, 31, v198
	v_lshl_add_u64 v[4:5], s[0:1], 0, v[198:199]
	v_lshlrev_b64 v[4:5], 7, v[4:5]
	v_lshl_add_u64 v[4:5], v[186:187], 0, v[4:5]
	global_load_dwordx4 v[128:131], v[4:5], off
	global_load_dwordx4 v[124:127], v[4:5], off offset:32
	global_load_dwordx4 v[120:123], v[4:5], off offset:64
	global_load_dwordx4 v[116:119], v[4:5], off offset:96

; __device__ __forceinline__ unsigned pk2(float lo, float hi) { return pg8::cvt_pk_bf16(lo, hi); }
; #define ATT_LOAD_Q(dst, J, set) do { const int qp_ = (J).pos0 + (32 * (set) + qc) * (J).d; _Pragma("unroll") for (int kk_ = 0; kk_ < 4; ++kk_) dst[kk_] = gld<bf16x8>(Qa + ((J).hb + (size_t)qp_) * 64 + 8 * h + 16 * kk_); } while (0)
; __device__ __forceinline__ void att_block(const bf16x8 (&kf)[4], const bf16x8 (&qf)[4], const bf16x8 (&va)[4], f32x16& o0, f32x16& o1, float& mrun, float& lrun, bool domask, int lo_, int hi_) {
;     f32x16 st;
; #pragma unroll
;     for (int i = 0; i < 16; ++i) st[i] = 0.f;
; #pragma unroll
;     for (int kk = 0; kk < 4; ++kk) st = __builtin_amdgcn_mfma_f32_32x32x16_bf16(kf[kk], qf[kk], st, 0, 0, 0);
;     if (domask) {
;         asm volatile("" : "+v"(lo_), "+v"(hi_));
; #pragma unroll
;         for (int i = 0; i < 16; ++i) { const int ci = (i & 3) + 8 * (i >> 2); st[i] = ((ci - lo_) | (hi_ - ci)) < 0 ? -INFINITY : st[i]; }
;     }
;     float bmax = -INFINITY;
; #pragma unroll
;     for (int i = 0; i < 16; ++i) bmax = fmaxf(bmax, st[i]);
;     bmax = fmaxf(bmax, __shfl_xor(bmax, 32));
;     const float mnew = fmaxf(mrun, bmax);
;     float lsum = 0.f;
; #pragma unroll
;     for (int i = 0; i < 16; ++i) { st[i] = __builtin_amdgcn_exp2f(st[i] - mnew); lsum += st[i]; }
;     lsum += __shfl_xor(lsum, 32);
;     const float alpha = __builtin_amdgcn_exp2f(mrun - mnew);
;     lrun = lrun * alpha + lsum; mrun = mnew;
; #pragma unroll
;     for (int i = 0; i < 16; ++i) { o0[i] *= alpha; o1[i] *= alpha; }
; #pragma unroll
;     for (int s = 0; s < 2; ++s) { v4u w; w.x = pk2(st[8 * s], st[8 * s + 1]); w.y = pk2(st[8 * s + 2], st[8 * s + 3]); w.z = pk2(st[8 * s + 4], st[8 * s + 5]); w.w = pk2(st[8 * s + 6], st[8 * s + 7]);
;         const bf16x8 pb = __builtin_bit_cast(bf16x8, w);
;         o0 = __builtin_amdgcn_mfma_f32_32x32x16_bf16(va[2 * s], pb, o0, 0, 0, 0);
;         o1 = __builtin_amdgcn_mfma_f32_32x32x16_bf16(va[2 * s + 1], pb, o1, 0, 0, 0); }
; }
; __device__ __forceinline__ void att_phase(unsigned char* ws, LAS unsigned char* lds, int lane, int wave, int G) {
;     ...
;             if (kb >= 1) {
;                 att_block(kf, qfB, va, oB0, oB1, mB, lB, kb == 1 || kb == 5 || kminB > 32 * (kb - 1), mloB - 4 * h - 32 * (kb - 1), qc + 128 - 4 * h - 32 * (kb - 1));
;                 if (kb == 5 && hn) ATT_LOAD_Q(qfB, N, 1);
.LBB0_96:
	ds_read_b128 v[68:71], v225 offset:4096
	ds_read_b128 v[132:135], v226 offset:4096
	ds_read_b128 v[136:139], v227 offset:4096
	ds_read_b128 v[140:143], v228 offset:4096
	ds_read_b64_tr_b16 v[92:93], v229 offset:12288
	ds_read_b64_tr_b16 v[94:95], v229 offset:13312
	ds_read_b64_tr_b16 v[86:87], v229 offset:13376
	ds_read_b64_tr_b16 v[84:85], v229 offset:12352
	s_waitcnt lgkmcnt(0)
	v_mfma_f32_32x32x16_bf16 v[68:83], v[68:71], v[112:115], 0
	ds_read_b64_tr_b16 v[96:97], v229 offset:14336
	ds_read_b64_tr_b16 v[98:99], v229 offset:15360
	ds_read_b64_tr_b16 v[90:91], v229 offset:15424
	ds_read_b64_tr_b16 v[88:89], v229 offset:14400
	s_mov_b32 s14, 0xff800000
	v_mfma_f32_32x32x16_bf16 v[68:83], v[132:135], v[108:111], v[68:83]
	v_mfma_f32_32x32x16_bf16 v[68:83], v[136:139], v[104:107], v[68:83]
	v_mfma_f32_32x32x16_bf16 v[68:83], v[140:143], v[100:103], v[68:83]
	s_nop 11
	s_mov_b32 vcc_lo, 0xffffffff
	s_mov_b32 vcc_hi, 0xfffffff0
	s_mov_b32 s24, 0xfffffffe
	s_mov_b32 s25, 0xffffffe0
	s_mov_b32 s26, 0xfffffffc
	s_mov_b32 s27, 0xffffffc0
	s_mov_b32 s28, 0xfffffff8
	s_mov_b32 s29, 0xffffff80
	v_cndmask_b32_e32 v68, v211, v68, vcc
	s_mov_b32 vcc_lo, 0xffffff00
	s_mov_b32 vcc_hi, 0xfffff000
	v_cndmask_b32_e64 v69, v211, v69, s[24:25]
	s_mov_b32 s24, 0xfffffe00
	s_mov_b32 s25, 0xffffe000
	v_cndmask_b32_e64 v70, v211, v70, s[26:27]
	s_mov_b32 s26, 0xfffffc00
	s_mov_b32 s27, 0xffffc000
	v_cndmask_b32_e64 v71, v211, v71, s[28:29]
	s_mov_b32 s28, 0xfffff800
	s_mov_b32 s29, 0xffff8000
	v_cndmask_b32_e32 v72, v211, v72, vcc
	s_mov_b32 vcc_lo, 0xffff0000
	s_mov_b32 vcc_hi, 0xfff00000
	v_cndmask_b32_e64 v73, v211, v73, s[24:25]
	s_mov_b32 s24, 0xfffe0000
	s_mov_b32 s25, 0xffe00000
	v_cndmask_b32_e64 v74, v211, v74, s[26:27]
	s_mov_b32 s26, 0xfffc0000
	s_mov_b32 s27, 0xffc00000
	v_cndmask_b32_e64 v75, v211, v75, s[28:29]
	s_mov_b32 s28, 0xfff80000
	s_mov_b32 s29, 0xff800000
	v_cndmask_b32_e32 v132, v211, v76, vcc
	s_mov_b32 vcc_lo, 0xff000000
	s_mov_b32 vcc_hi, 0xf0000000
	v_cndmask_b32_e64 v77, v211, v77, s[24:25]
	s_mov_b32 s24, 0xfe000000
	s_mov_b32 s25, 0xe0000000
	v_cndmask_b32_e64 v78, v211, v78, s[26:27]
	s_mov_b32 s26, 0xfc000000
	s_mov_b32 s27, 0xc0000000
	v_cndmask_b32_e64 v79, v211, v79, s[28:29]
	s_mov_b32 s28, 0xf8000000
	s_mov_b32 s29, 0x80000000
	v_cndmask_b32_e32 v80, v211, v80, vcc
	v_cndmask_b32_e64 v81, v211, v81, s[24:25]
	v_cndmask_b32_e64 v82, v211, v82, s[26:27]
	v_cndmask_b32_e64 v83, v211, v83, s[28:29]
	s_nop 0
	s_nop 1
	s_nop 1
	s_nop 0
	v_max3_f32 v76, v68, s14, v69
	v_max3_f32 v76, v76, v70, v71
	v_max3_f32 v76, v76, v72, v73
	v_max3_f32 v76, v76, v74, v75
	v_max3_f32 v76, v76, v132, v77
	v_max3_f32 v76, v76, v78, v79
	v_max3_f32 v76, v76, v80, v81
	v_max3_f32 v76, v76, v82, v83
	ds_bpermute_b32 v133, v201, v76
	s_and_b64 vcc, exec, s[6:7]
	s_waitcnt lgkmcnt(0)
	v_max3_f32 v76, v151, v76, v133
	v_sub_f32_e32 v68, v68, v76
	v_exp_f32_e32 v68, v68
	v_sub_f32_e32 v69, v69, v76
	v_exp_f32_e32 v69, v69
	v_sub_f32_e32 v70, v70, v76
	v_exp_f32_e32 v70, v70
	v_sub_f32_e32 v71, v71, v76
	v_exp_f32_e32 v71, v71
	v_sub_f32_e32 v72, v72, v76
	v_exp_f32_e32 v72, v72
	v_sub_f32_e32 v73, v73, v76
	v_add_f32_e32 v133, v69, v68
	v_exp_f32_e32 v73, v73
	v_sub_f32_e32 v74, v74, v76
	v_add_f32_e32 v133, v70, v133
	v_exp_f32_e32 v74, v74
	v_sub_f32_e32 v75, v75, v76
	v_add_f32_e32 v133, v71, v133
	v_exp_f32_e32 v75, v75
	v_sub_f32_e32 v132, v132, v76
	v_add_f32_e32 v133, v72, v133
	v_exp_f32_e32 v132, v132
	v_sub_f32_e32 v77, v77, v76
	v_add_f32_e32 v133, v73, v133
	v_exp_f32_e32 v77, v77
	v_sub_f32_e32 v78, v78, v76
	v_add_f32_e32 v133, v74, v133
	v_exp_f32_e32 v134, v78
	v_add_f32_e32 v78, v75, v133
	v_add_f32_e32 v78, v132, v78
	v_add_f32_e32 v78, v77, v78
	v_add_f32_e32 v133, v134, v78
	v_sub_f32_e32 v78, v79, v76
	v_exp_f32_e32 v79, v78
	v_sub_f32_e32 v78, v80, v76
	v_exp_f32_e32 v80, v78
	v_sub_f32_e32 v78, v151, v76
	v_exp_f32_e32 v78, v78
	v_cvt_pk_bf16_f32 v68, v68, v69
	v_cvt_pk_bf16_f32 v69, v70, v71
	v_cvt_pk_bf16_f32 v70, v72, v73
	v_pk_mul_f32 v[34:35], v[34:35], v[78:79] op_sel_hi:[1,0]
	v_pk_mul_f32 v[32:33], v[32:33], v[78:79] op_sel_hi:[1,0]
	v_pk_mul_f32 v[30:31], v[30:31], v[78:79] op_sel_hi:[1,0]
	v_pk_mul_f32 v[28:29], v[28:29], v[78:79] op_sel_hi:[1,0]
	v_pk_mul_f32 v[26:27], v[26:27], v[78:79] op_sel_hi:[1,0]
	v_pk_mul_f32 v[24:25], v[24:25], v[78:79] op_sel_hi:[1,0]
	v_pk_mul_f32 v[22:23], v[22:23], v[78:79] op_sel_hi:[1,0]
	v_pk_mul_f32 v[20:21], v[20:21], v[78:79] op_sel_hi:[1,0]
	v_pk_mul_f32 v[18:19], v[18:19], v[78:79] op_sel_hi:[1,0]
	v_cvt_pk_bf16_f32 v71, v74, v75
	v_pk_mul_f32 v[16:17], v[16:17], v[78:79] op_sel_hi:[1,0]
	v_pk_mul_f32 v[14:15], v[14:15], v[78:79] op_sel_hi:[1,0]
	v_pk_mul_f32 v[12:13], v[12:13], v[78:79] op_sel_hi:[1,0]
	v_pk_mul_f32 v[10:11], v[10:11], v[78:79] op_sel_hi:[1,0]
	v_pk_mul_f32 v[8:9], v[8:9], v[78:79] op_sel_hi:[1,0]
	v_pk_mul_f32 v[6:7], v[6:7], v[78:79] op_sel_hi:[1,0]
	v_pk_mul_f32 v[4:5], v[4:5], v[78:79] op_sel_hi:[1,0]
	v_mfma_f32_32x32x16_bf16 v[20:35], v[92:95], v[68:71], v[20:35]
	v_sub_f32_e32 v81, v81, v76
	v_sub_f32_e32 v82, v82, v76
	v_exp_f32_e32 v81, v81
	v_exp_f32_e32 v72, v82
	v_add_f32_e32 v74, v79, v133
	v_add_f32_e32 v74, v80, v74
	v_add_f32_e32 v74, v81, v74
	v_mfma_f32_32x32x16_bf16 v[4:19], v[84:87], v[68:71], v[4:19]
	v_sub_f32_e32 v68, v83, v76
	v_exp_f32_e32 v73, v68
	v_cvt_pk_bf16_f32 v68, v132, v77
	v_cvt_pk_bf16_f32 v69, v134, v79
	v_cvt_pk_bf16_f32 v70, v80, v81
	v_cvt_pk_bf16_f32 v71, v72, v73
	v_add_f32_e32 v72, v72, v74
	v_add_f32_e32 v77, v73, v72
	v_mfma_f32_32x32x16_bf16 v[20:35], v[96:99], v[68:71], v[20:35]
	ds_bpermute_b32 v79, v201, v77
	v_mfma_f32_32x32x16_bf16 v[4:19], v[88:91], v[68:71], v[4:19]
	s_cbranch_vccnz .LBB0_98
	v_lshl_add_u32 v68, s52, 5, v198
	v_ashrrev_i32_e32 v69, 31, v68
	v_lshl_add_u64 v[68:69], s[0:1], 0, v[68:69]
	v_lshlrev_b64 v[68:69], 7, v[68:69]
	v_lshl_add_u64 v[68:69], v[186:187], 0, v[68:69]
	global_load_dwordx4 v[112:115], v[68:69], off
	global_load_dwordx4 v[108:111], v[68:69], off offset:32
	global_load_dwordx4 v[104:107], v[68:69], off offset:64
	global_load_dwordx4 v[100:103], v[68:69], off offset:96
